# v49 plus scalar bookkeeping moved out of the post-barrier heads of the attention steps (dead s_movs dropped, slot rotation computed before the barrier)
# speedup vs baseline: 1.0018x; 1.0018x over previous
; #define WAIT_BAR(N) asm volatile("s_waitcnt vmcnt(" #N ") lgkmcnt(0)\n\ts_barrier":::"memory")
;   #define RESC() do{ if(resc){ asm volatile("s_waitcnt lgkmcnt(0)":::"memory"); \
;       _Pragma("unroll") for(int d_=0;d_<2;++d_) _Pragma("unroll") for(int r=0;r<16;++r)o[d_][r]*=wsf[crow(r,hi)]; } }while(0)
;   #define ROT() do{sl_prev=sl_cur;sl_cur=sl_next;sl_next=(sl_next==(NSLOT-1)*SLOTB)?0:sl_next+SLOTB;}while(0)
; template<int THRL> __device__ __forceinline__ void attn_unit(const bf16*Qu,const bf16*__restrict__ Kh,const bf16*__restrict__ Vh,bf16*Ou,const int NT,const float shift,char*shm){
;     ...
;   int t=1;
;     ...
;   for(;t+5<NT;t+=2){
;     STEP(pB0,pB1,pA0,pA1,t,true,true,true);     WAIT_BAR(2); RESC(); ROT();
.LBB0_618:
	ds_read_b64_tr_b16 v[52:53], v199 offset:24576
	ds_read_b64_tr_b16 v[54:55], v199 offset:25088
	v_mfma_f32_32x32x16_bf16 v[114:129], v[190:193], v[150:153], v[34:49]
	v_add_f32_e32 v50, v82, v50
	v_add_f32_e32 v194, v83, v194
	v_add_f32_e32 v195, v84, v195
	v_add_f32_e32 v196, v85, v196
	v_add_f32_e32 v50, v86, v50
	v_add_f32_e32 v194, v87, v194
	v_cvt_pk_bf16_f32 v158, v82, v83
	v_cvt_pk_bf16_f32 v159, v84, v85
	ds_read_b64_tr_b16 v[60:61], v199 offset:28672
	ds_read_b64_tr_b16 v[62:63], v199 offset:29184
	v_mfma_f32_32x32x16_bf16 v[98:113], v[186:189], v[150:153], v[34:49]
	v_add_f32_e32 v195, v88, v195
	v_add_f32_e32 v196, v89, v196
	v_add_f32_e32 v50, v90, v50
	v_add_f32_e32 v194, v91, v194
	v_cvt_pk_bf16_f32 v160, v86, v87
	v_cvt_pk_bf16_f32 v161, v88, v89
	ds_read_b64_tr_b16 v[82:83], v199 offset:25600
	ds_read_b64_tr_b16 v[84:85], v199 offset:26112
	v_mfma_f32_32x32x16_bf16 v[114:129], v[182:185], v[138:141], v[114:129]
	v_add_f32_e32 v195, v92, v195
	v_add_f32_e32 v196, v93, v196
	v_add_f32_e32 v50, v94, v50
	v_add_f32_e32 v194, v95, v194
	v_cvt_pk_bf16_f32 v154, v90, v91
	v_cvt_pk_bf16_f32 v155, v92, v93
	ds_read_b64_tr_b16 v[86:87], v199 offset:29696
	ds_read_b64_tr_b16 v[88:89], v199 offset:30208
	v_mfma_f32_32x32x16_bf16 v[98:113], v[178:181], v[138:141], v[98:113]
	v_add_f32_e32 v195, v96, v195
	v_add_f32_e32 v196, v97, v196
	v_add_f32_e32 v50, v66, v50
	v_add_f32_e32 v194, v67, v194
	v_cvt_pk_bf16_f32 v156, v94, v95
	v_cvt_pk_bf16_f32 v157, v96, v97
	ds_read_b64_tr_b16 v[90:91], v199 offset:26624
	ds_read_b64_tr_b16 v[92:93], v199 offset:27136
	v_mfma_f32_32x32x16_bf16 v[114:129], v[174:177], v[134:137], v[114:129]
	v_add_f32_e32 v195, v68, v195
	v_add_f32_e32 v196, v69, v196
	v_add_f32_e32 v50, v70, v50
	v_add_f32_e32 v194, v71, v194
	v_cvt_pk_bf16_f32 v146, v66, v67
	v_cvt_pk_bf16_f32 v147, v68, v69
	ds_read_b64_tr_b16 v[64:65], v199 offset:30720
	ds_read_b64_tr_b16 v[66:67], v199 offset:31232
	v_mfma_f32_32x32x16_bf16 v[98:113], v[170:173], v[134:137], v[98:113]
	v_add_f32_e32 v195, v72, v195
	v_add_f32_e32 v196, v73, v196
	v_add_f32_e32 v50, v74, v50
	v_add_f32_e32 v194, v75, v194
	v_cvt_pk_bf16_f32 v148, v70, v71
	v_cvt_pk_bf16_f32 v149, v72, v73
	ds_read_b64_tr_b16 v[68:69], v199 offset:27648
	ds_read_b64_tr_b16 v[70:71], v199 offset:28160
	v_mfma_f32_32x32x16_bf16 v[114:129], v[166:169], v[130:133], v[114:129]
	v_add_f32_e32 v195, v76, v195
	v_add_f32_e32 v196, v77, v196
	v_add_f32_e32 v50, v78, v50
	v_add_f32_e32 v194, v79, v194
	v_cvt_pk_bf16_f32 v142, v74, v75
	v_cvt_pk_bf16_f32 v143, v76, v77
	ds_read_b64_tr_b16 v[72:73], v199 offset:31744
	ds_read_b64_tr_b16 v[74:75], v199 offset:32256
	v_mfma_f32_32x32x16_bf16 v[98:113], v[162:165], v[130:133], v[98:113]
	v_add_f32_e32 v195, v80, v195
	v_add_f32_e32 v196, v81, v196
	v_cvt_pk_bf16_f32 v144, v78, v79
	v_cvt_pk_bf16_f32 v145, v80, v81
	s_add_i32 s6, s31, s70
	s_mov_b32 s7, m0
	s_mov_b32 m0, s6
	s_nop 0
	global_load_lds_dwordx4 v197, s[98:99]
	s_mov_b32 m0, s7
	s_add_i32 s6, s76, s71
	s_mov_b32 s7, m0
	s_mov_b32 m0, s6
	s_nop 0
	global_load_lds_dwordx4 v197, s[100:101]
	s_mov_b32 m0, s7
	s_add_u32 s98, s98, 0x2000
	s_addc_u32 s99, s99, 0
	s_add_u32 s100, s100, 0x2000
	s_addc_u32 s101, s101, 0
	s_waitcnt lgkmcnt(14)
	v_mfma_f32_32x32x16_bf16 v[2:17], v[158:161], v[52:55], v[2:17]
	v_exp_f32_e32 v114, v114
	v_exp_f32_e32 v115, v115
	v_exp_f32_e32 v116, v116
	v_exp_f32_e32 v117, v117
	s_waitcnt lgkmcnt(12)
	v_mfma_f32_32x32x16_bf16 v[18:33], v[158:161], v[60:63], v[18:33]
	v_exp_f32_e32 v118, v118
	v_exp_f32_e32 v119, v119
	v_exp_f32_e32 v120, v120
	v_exp_f32_e32 v121, v121
	ds_read_b128 v[60:63], v204
	ds_read_b128 v[162:165], v204 offset:512
	s_waitcnt lgkmcnt(12)
	v_mfma_f32_32x32x16_bf16 v[2:17], v[154:157], v[82:85], v[2:17]
	v_exp_f32_e32 v122, v122
	v_exp_f32_e32 v123, v123
	v_exp_f32_e32 v124, v124
	v_exp_f32_e32 v125, v125
	ds_read_b128 v[166:169], v204 offset:2048
	ds_read_b128 v[170:173], v204 offset:2560
	s_waitcnt lgkmcnt(12)
	v_mfma_f32_32x32x16_bf16 v[18:33], v[154:157], v[86:89], v[18:33]
	v_exp_f32_e32 v126, v126
	v_exp_f32_e32 v127, v127
	v_exp_f32_e32 v128, v128
	v_exp_f32_e32 v129, v129
	ds_read_b128 v[174:177], v204 offset:4096
	ds_read_b128 v[178:181], v204 offset:4608
	s_waitcnt lgkmcnt(12)
	v_mfma_f32_32x32x16_bf16 v[2:17], v[146:149], v[90:93], v[2:17]
	v_exp_f32_e32 v98, v98
	v_exp_f32_e32 v99, v99
	v_exp_f32_e32 v100, v100
	v_exp_f32_e32 v101, v101
	ds_read_b128 v[182:185], v204 offset:6144
	ds_read_b128 v[52:55], v204 offset:6656
	s_waitcnt lgkmcnt(12)
	v_mfma_f32_32x32x16_bf16 v[18:33], v[146:149], v[64:67], v[18:33]
	v_exp_f32_e32 v102, v102
	v_exp_f32_e32 v103, v103
	v_exp_f32_e32 v104, v104
	v_exp_f32_e32 v105, v105
	s_waitcnt lgkmcnt(10)
	v_mfma_f32_32x32x16_bf16 v[2:17], v[142:145], v[68:71], v[2:17]
	v_exp_f32_e32 v106, v106
	v_exp_f32_e32 v107, v107
	v_exp_f32_e32 v108, v108
	v_exp_f32_e32 v109, v109
	s_waitcnt lgkmcnt(8)
	v_mfma_f32_32x32x16_bf16 v[18:33], v[142:145], v[72:75], v[18:33]
	v_exp_f32_e32 v110, v110
	v_exp_f32_e32 v111, v111
	v_exp_f32_e32 v112, v112
	v_exp_f32_e32 v113, v113
	s_add_i32 s6, s76, 0x2000
	s_cmpk_lg_i32 s76, 0x4000
	s_cselect_b32 s31, s6, 0
	s_waitcnt vmcnt(2) lgkmcnt(0)
	s_barrier
; #define WAIT_BAR(N) asm volatile("s_waitcnt vmcnt(" #N ") lgkmcnt(0)\n\ts_barrier":::"memory")
;   #define RESC() do{ if(resc){ asm volatile("s_waitcnt lgkmcnt(0)":::"memory"); \
;       _Pragma("unroll") for(int d_=0;d_<2;++d_) _Pragma("unroll") for(int r=0;r<16;++r)o[d_][r]*=wsf[crow(r,hi)]; } }while(0)
;   #define ROT() do{sl_prev=sl_cur;sl_cur=sl_next;sl_next=(sl_next==(NSLOT-1)*SLOTB)?0:sl_next+SLOTB;}while(0)
; template<int THRL> __device__ __forceinline__ void attn_unit(const bf16*Qu,const bf16*__restrict__ Kh,const bf16*__restrict__ Vh,bf16*Ou,const int NT,const float shift,char*shm){
;     ...
;   int t=1;
;     ...
;   for(;t+5<NT;t+=2){
;     STEP(pB0,pB1,pA0,pA1,t,true,true,true);     WAIT_BAR(2); RESC(); ROT();
	ds_read_b64_tr_b16 v[186:187], v200 offset:24576
	ds_read_b64_tr_b16 v[188:189], v200 offset:25088
	v_mfma_f32_32x32x16_bf16 v[82:97], v[60:63], v[150:153], v[34:49]
	v_add_f32_e32 v50, v114, v50
	v_add_f32_e32 v194, v115, v194
	v_add_f32_e32 v195, v116, v195
	v_add_f32_e32 v196, v117, v196
	v_add_f32_e32 v50, v118, v50
	v_add_f32_e32 v194, v119, v194
	v_cvt_pk_bf16_f32 v158, v114, v115
	v_cvt_pk_bf16_f32 v159, v116, v117
	ds_read_b64_tr_b16 v[60:61], v200 offset:28672
	ds_read_b64_tr_b16 v[62:63], v200 offset:29184
	v_mfma_f32_32x32x16_bf16 v[66:81], v[162:165], v[150:153], v[34:49]
	v_add_f32_e32 v195, v120, v195
	v_add_f32_e32 v196, v121, v196
	v_add_f32_e32 v50, v122, v50
	v_add_f32_e32 v194, v123, v194
	v_cvt_pk_bf16_f32 v160, v118, v119
	v_cvt_pk_bf16_f32 v161, v120, v121
	ds_read_b64_tr_b16 v[114:115], v200 offset:25600
	ds_read_b64_tr_b16 v[116:117], v200 offset:26112
	v_mfma_f32_32x32x16_bf16 v[82:97], v[166:169], v[138:141], v[82:97]
	v_add_f32_e32 v195, v124, v195
	v_add_f32_e32 v196, v125, v196
	v_add_f32_e32 v50, v126, v50
	v_add_f32_e32 v194, v127, v194
	v_cvt_pk_bf16_f32 v154, v122, v123
	v_cvt_pk_bf16_f32 v155, v124, v125
	ds_read_b64_tr_b16 v[118:119], v200 offset:29696
	ds_read_b64_tr_b16 v[120:121], v200 offset:30208
	v_mfma_f32_32x32x16_bf16 v[66:81], v[170:173], v[138:141], v[66:81]
	v_add_f32_e32 v195, v128, v195
	v_add_f32_e32 v196, v129, v196
	v_add_f32_e32 v50, v98, v50
	v_add_f32_e32 v194, v99, v194
	v_cvt_pk_bf16_f32 v156, v126, v127
	v_cvt_pk_bf16_f32 v157, v128, v129
	ds_read_b64_tr_b16 v[122:123], v200 offset:26624
	ds_read_b64_tr_b16 v[124:125], v200 offset:27136
	v_mfma_f32_32x32x16_bf16 v[82:97], v[174:177], v[134:137], v[82:97]
	v_add_f32_e32 v195, v100, v195
	v_add_f32_e32 v196, v101, v196
	v_add_f32_e32 v50, v102, v50
	v_add_f32_e32 v194, v103, v194
	v_cvt_pk_bf16_f32 v146, v98, v99
	v_cvt_pk_bf16_f32 v147, v100, v101
	ds_read_b64_tr_b16 v[98:99], v200 offset:30720
	ds_read_b64_tr_b16 v[100:101], v200 offset:31232
	v_mfma_f32_32x32x16_bf16 v[66:81], v[178:181], v[134:137], v[66:81]
	v_add_f32_e32 v195, v104, v195
	v_add_f32_e32 v196, v105, v196
	v_add_f32_e32 v50, v106, v50
	v_add_f32_e32 v194, v107, v194
	v_cvt_pk_bf16_f32 v148, v102, v103
	v_cvt_pk_bf16_f32 v149, v104, v105
	ds_read_b64_tr_b16 v[102:103], v200 offset:27648
	ds_read_b64_tr_b16 v[104:105], v200 offset:28160
	v_mfma_f32_32x32x16_bf16 v[82:97], v[182:185], v[130:133], v[82:97]
	v_add_f32_e32 v195, v108, v195
	v_add_f32_e32 v196, v109, v196
	v_add_f32_e32 v50, v110, v50
	v_add_f32_e32 v194, v111, v194
	v_cvt_pk_bf16_f32 v142, v106, v107
	v_cvt_pk_bf16_f32 v143, v108, v109
	ds_read_b64_tr_b16 v[106:107], v200 offset:31744
	ds_read_b64_tr_b16 v[108:109], v200 offset:32256
	v_mfma_f32_32x32x16_bf16 v[66:81], v[52:55], v[130:133], v[66:81]
	v_add_f32_e32 v195, v112, v195
	v_add_f32_e32 v196, v113, v196
	v_cvt_pk_bf16_f32 v144, v110, v111
	v_cvt_pk_bf16_f32 v145, v112, v113
	s_add_i32 s6, s76, s70
	s_mov_b32 s7, m0
	s_mov_b32 m0, s6
	s_nop 0
	global_load_lds_dwordx4 v197, s[98:99]
	s_mov_b32 m0, s7
	s_add_i32 s6, s31, s71
	s_mov_b32 s7, m0
	s_mov_b32 m0, s6
	s_nop 0
	global_load_lds_dwordx4 v197, s[100:101]
	s_mov_b32 m0, s7
	s_add_u32 s98, s98, 0x2000
	s_addc_u32 s99, s99, 0
	s_add_u32 s100, s100, 0x2000
	s_addc_u32 s101, s101, 0
	s_waitcnt lgkmcnt(14)
	v_mfma_f32_32x32x16_bf16 v[2:17], v[158:161], v[186:189], v[2:17]
	v_exp_f32_e32 v82, v82
	v_exp_f32_e32 v83, v83
	v_exp_f32_e32 v84, v84
	v_exp_f32_e32 v85, v85
	s_waitcnt lgkmcnt(12)
	v_mfma_f32_32x32x16_bf16 v[18:33], v[158:161], v[60:63], v[18:33]
	v_exp_f32_e32 v86, v86
	v_exp_f32_e32 v87, v87
	v_exp_f32_e32 v88, v88
	v_exp_f32_e32 v89, v89
	ds_read_b128 v[190:193], v202
	ds_read_b128 v[186:189], v202 offset:512
	s_waitcnt lgkmcnt(12)
	v_mfma_f32_32x32x16_bf16 v[2:17], v[154:157], v[114:117], v[2:17]
	v_exp_f32_e32 v90, v90
	v_exp_f32_e32 v91, v91
	v_exp_f32_e32 v92, v92
	v_exp_f32_e32 v93, v93
	ds_read_b128 v[182:185], v202 offset:2048
	ds_read_b128 v[178:181], v202 offset:2560
	s_waitcnt lgkmcnt(12)
	v_mfma_f32_32x32x16_bf16 v[18:33], v[154:157], v[118:121], v[18:33]
	v_exp_f32_e32 v94, v94
	v_exp_f32_e32 v95, v95
	v_exp_f32_e32 v96, v96
	v_exp_f32_e32 v97, v97
	ds_read_b128 v[174:177], v202 offset:4096
	ds_read_b128 v[170:173], v202 offset:4608
	s_waitcnt lgkmcnt(12)
	v_mfma_f32_32x32x16_bf16 v[2:17], v[146:149], v[122:125], v[2:17]
	v_exp_f32_e32 v66, v66
	v_exp_f32_e32 v67, v67
	v_exp_f32_e32 v68, v68
	v_exp_f32_e32 v69, v69
	ds_read_b128 v[166:169], v202 offset:6144
	ds_read_b128 v[162:165], v202 offset:6656
	s_waitcnt lgkmcnt(12)
	v_mfma_f32_32x32x16_bf16 v[18:33], v[146:149], v[98:101], v[18:33]
	v_exp_f32_e32 v70, v70
	v_exp_f32_e32 v71, v71
	v_exp_f32_e32 v72, v72
	v_exp_f32_e32 v73, v73
	s_waitcnt lgkmcnt(10)
	v_mfma_f32_32x32x16_bf16 v[2:17], v[142:145], v[102:105], v[2:17]
	v_exp_f32_e32 v74, v74
	v_exp_f32_e32 v75, v75
	v_exp_f32_e32 v76, v76
	v_exp_f32_e32 v77, v77
	s_waitcnt lgkmcnt(8)
	v_mfma_f32_32x32x16_bf16 v[18:33], v[142:145], v[106:109], v[18:33]
	v_exp_f32_e32 v78, v78
	v_exp_f32_e32 v79, v79
	v_exp_f32_e32 v80, v80
	v_exp_f32_e32 v81, v81
	s_add_i32 s6, s31, 0x2000
	s_cmpk_lg_i32 s31, 0x4000
	s_mov_b32 s24, s76
	s_cselect_b32 s76, s6, 0
	s_add_i32 s26, s26, 2
	s_cmp_gt_i32 s26, s91
	s_cbranch_scc1 .Lattn_exit
	s_waitcnt vmcnt(2) lgkmcnt(0)
	s_barrier
; #define WAIT_BAR(N) asm volatile("s_waitcnt vmcnt(" #N ") lgkmcnt(0)\n\ts_barrier":::"memory")
;   #define RESC() do{ if(resc){ asm volatile("s_waitcnt lgkmcnt(0)":::"memory"); \
;       _Pragma("unroll") for(int d_=0;d_<2;++d_) _Pragma("unroll") for(int r=0;r<16;++r)o[d_][r]*=wsf[crow(r,hi)]; } }while(0)
;   #define ROT() do{sl_prev=sl_cur;sl_cur=sl_next;sl_next=(sl_next==(NSLOT-1)*SLOTB)?0:sl_next+SLOTB;}while(0)
; template<int THRL> __device__ __forceinline__ void attn_unit(const bf16*Qu,const bf16*__restrict__ Kh,const bf16*__restrict__ Vh,bf16*Ou,const int NT,const float shift,char*shm){
;     ...
;   int t=1;
;     ...
;   for(;t+5<NT;t+=2){
;     STEP(pB0,pB1,pA0,pA1,t,true,true,true);     WAIT_BAR(2); RESC(); ROT();
.Lattn_cpB:
	ds_read_b64_tr_b16 v[52:53], v201 offset:24576
	ds_read_b64_tr_b16 v[54:55], v201 offset:25088
	v_mfma_f32_32x32x16_bf16 v[114:129], v[190:193], v[150:153], v[34:49]
	v_add_f32_e32 v50, v82, v50
	v_add_f32_e32 v194, v83, v194
	v_add_f32_e32 v195, v84, v195
	v_add_f32_e32 v196, v85, v196
	v_add_f32_e32 v50, v86, v50
	v_add_f32_e32 v194, v87, v194
	v_cvt_pk_bf16_f32 v158, v82, v83
	v_cvt_pk_bf16_f32 v159, v84, v85
	ds_read_b64_tr_b16 v[60:61], v201 offset:28672
	ds_read_b64_tr_b16 v[62:63], v201 offset:29184
	v_mfma_f32_32x32x16_bf16 v[98:113], v[186:189], v[150:153], v[34:49]
	v_add_f32_e32 v195, v88, v195
	v_add_f32_e32 v196, v89, v196
	v_add_f32_e32 v50, v90, v50
	v_add_f32_e32 v194, v91, v194
	v_cvt_pk_bf16_f32 v160, v86, v87
	v_cvt_pk_bf16_f32 v161, v88, v89
	ds_read_b64_tr_b16 v[82:83], v201 offset:25600
	ds_read_b64_tr_b16 v[84:85], v201 offset:26112
	v_mfma_f32_32x32x16_bf16 v[114:129], v[182:185], v[138:141], v[114:129]
	v_add_f32_e32 v195, v92, v195
	v_add_f32_e32 v196, v93, v196
	v_add_f32_e32 v50, v94, v50
	v_add_f32_e32 v194, v95, v194
	v_cvt_pk_bf16_f32 v154, v90, v91
	v_cvt_pk_bf16_f32 v155, v92, v93
	ds_read_b64_tr_b16 v[86:87], v201 offset:29696
	ds_read_b64_tr_b16 v[88:89], v201 offset:30208
	v_mfma_f32_32x32x16_bf16 v[98:113], v[178:181], v[138:141], v[98:113]
	v_add_f32_e32 v195, v96, v195
	v_add_f32_e32 v196, v97, v196
	v_add_f32_e32 v50, v66, v50
	v_add_f32_e32 v194, v67, v194
	v_cvt_pk_bf16_f32 v156, v94, v95
	v_cvt_pk_bf16_f32 v157, v96, v97
	ds_read_b64_tr_b16 v[90:91], v201 offset:26624
	ds_read_b64_tr_b16 v[92:93], v201 offset:27136
	v_mfma_f32_32x32x16_bf16 v[114:129], v[174:177], v[134:137], v[114:129]
	v_add_f32_e32 v195, v68, v195
	v_add_f32_e32 v196, v69, v196
	v_add_f32_e32 v50, v70, v50
	v_add_f32_e32 v194, v71, v194
	v_cvt_pk_bf16_f32 v146, v66, v67
	v_cvt_pk_bf16_f32 v147, v68, v69
	ds_read_b64_tr_b16 v[64:65], v201 offset:30720
	ds_read_b64_tr_b16 v[66:67], v201 offset:31232
	v_mfma_f32_32x32x16_bf16 v[98:113], v[170:173], v[134:137], v[98:113]
	v_add_f32_e32 v195, v72, v195
	v_add_f32_e32 v196, v73, v196
	v_add_f32_e32 v50, v74, v50
	v_add_f32_e32 v194, v75, v194
	v_cvt_pk_bf16_f32 v148, v70, v71
	v_cvt_pk_bf16_f32 v149, v72, v73
	ds_read_b64_tr_b16 v[68:69], v201 offset:27648
	ds_read_b64_tr_b16 v[70:71], v201 offset:28160
	v_mfma_f32_32x32x16_bf16 v[114:129], v[166:169], v[130:133], v[114:129]
	v_add_f32_e32 v195, v76, v195
	v_add_f32_e32 v196, v77, v196
	v_add_f32_e32 v50, v78, v50
	v_add_f32_e32 v194, v79, v194
	v_cvt_pk_bf16_f32 v142, v74, v75
	v_cvt_pk_bf16_f32 v143, v76, v77
	ds_read_b64_tr_b16 v[72:73], v201 offset:31744
	ds_read_b64_tr_b16 v[74:75], v201 offset:32256
	v_mfma_f32_32x32x16_bf16 v[98:113], v[162:165], v[130:133], v[98:113]
	v_add_f32_e32 v195, v80, v195
	v_add_f32_e32 v196, v81, v196
	v_cvt_pk_bf16_f32 v144, v78, v79
	v_cvt_pk_bf16_f32 v145, v80, v81
	s_add_i32 s6, s31, s70
	s_mov_b32 s7, m0
	s_mov_b32 m0, s6
	s_nop 0
	global_load_lds_dwordx4 v197, s[98:99]
	s_mov_b32 m0, s7
	s_add_i32 s6, s76, s71
	s_mov_b32 s7, m0
	s_mov_b32 m0, s6
	s_nop 0
	global_load_lds_dwordx4 v197, s[100:101]
	s_mov_b32 m0, s7
	s_add_u32 s98, s98, 0x2000
	s_addc_u32 s99, s99, 0
	s_add_u32 s100, s100, 0x2000
	s_addc_u32 s101, s101, 0
	s_waitcnt lgkmcnt(14)
	v_mfma_f32_32x32x16_bf16 v[2:17], v[158:161], v[52:55], v[2:17]
	v_exp_f32_e32 v114, v114
	v_exp_f32_e32 v115, v115
	v_exp_f32_e32 v116, v116
	v_exp_f32_e32 v117, v117
	s_waitcnt lgkmcnt(12)
	v_mfma_f32_32x32x16_bf16 v[18:33], v[158:161], v[60:63], v[18:33]
	v_exp_f32_e32 v118, v118
	v_exp_f32_e32 v119, v119
	v_exp_f32_e32 v120, v120
	v_exp_f32_e32 v121, v121
	ds_read_b128 v[60:63], v203
	ds_read_b128 v[162:165], v203 offset:512
	s_waitcnt lgkmcnt(12)
	v_mfma_f32_32x32x16_bf16 v[2:17], v[154:157], v[82:85], v[2:17]
	v_exp_f32_e32 v122, v122
	v_exp_f32_e32 v123, v123
	v_exp_f32_e32 v124, v124
	v_exp_f32_e32 v125, v125
	ds_read_b128 v[166:169], v203 offset:2048
	ds_read_b128 v[170:173], v203 offset:2560
	s_waitcnt lgkmcnt(12)
	v_mfma_f32_32x32x16_bf16 v[18:33], v[154:157], v[86:89], v[18:33]
	v_exp_f32_e32 v126, v126
	v_exp_f32_e32 v127, v127
	v_exp_f32_e32 v128, v128
	v_exp_f32_e32 v129, v129
	ds_read_b128 v[174:177], v203 offset:4096
	ds_read_b128 v[178:181], v203 offset:4608
	s_waitcnt lgkmcnt(12)
	v_mfma_f32_32x32x16_bf16 v[2:17], v[146:149], v[90:93], v[2:17]
	v_exp_f32_e32 v98, v98
	v_exp_f32_e32 v99, v99
	v_exp_f32_e32 v100, v100
	v_exp_f32_e32 v101, v101
	ds_read_b128 v[182:185], v203 offset:6144
	ds_read_b128 v[52:55], v203 offset:6656
	s_waitcnt lgkmcnt(12)
	v_mfma_f32_32x32x16_bf16 v[18:33], v[146:149], v[64:67], v[18:33]
	v_exp_f32_e32 v102, v102
	v_exp_f32_e32 v103, v103
	v_exp_f32_e32 v104, v104
	v_exp_f32_e32 v105, v105
	s_waitcnt lgkmcnt(10)
	v_mfma_f32_32x32x16_bf16 v[2:17], v[142:145], v[68:71], v[2:17]
	v_exp_f32_e32 v106, v106
	v_exp_f32_e32 v107, v107
	v_exp_f32_e32 v108, v108
	v_exp_f32_e32 v109, v109
	s_waitcnt lgkmcnt(8)
	v_mfma_f32_32x32x16_bf16 v[18:33], v[142:145], v[72:75], v[18:33]
	v_exp_f32_e32 v110, v110
	v_exp_f32_e32 v111, v111
	v_exp_f32_e32 v112, v112
	v_exp_f32_e32 v113, v113
	s_add_i32 s6, s76, 0x2000
	s_cmpk_lg_i32 s76, 0x4000
	s_cselect_b32 s31, s6, 0
	s_waitcnt vmcnt(2) lgkmcnt(0)
	s_barrier
; #define WAIT_BAR(N) asm volatile("s_waitcnt vmcnt(" #N ") lgkmcnt(0)\n\ts_barrier":::"memory")
;   #define RESC() do{ if(resc){ asm volatile("s_waitcnt lgkmcnt(0)":::"memory"); \
;       _Pragma("unroll") for(int d_=0;d_<2;++d_) _Pragma("unroll") for(int r=0;r<16;++r)o[d_][r]*=wsf[crow(r,hi)]; } }while(0)
;   #define ROT() do{sl_prev=sl_cur;sl_cur=sl_next;sl_next=(sl_next==(NSLOT-1)*SLOTB)?0:sl_next+SLOTB;}while(0)
; template<int THRL> __device__ __forceinline__ void attn_unit(const bf16*Qu,const bf16*__restrict__ Kh,const bf16*__restrict__ Vh,bf16*Ou,const int NT,const float shift,char*shm){
;     ...
;   int t=1;
;     ...
;   for(;t+5<NT;t+=2){
;     STEP(pB0,pB1,pA0,pA1,t,true,true,true);     WAIT_BAR(2); RESC(); ROT();
	ds_read_b64_tr_b16 v[186:187], v199 offset:24576
	ds_read_b64_tr_b16 v[188:189], v199 offset:25088
	v_mfma_f32_32x32x16_bf16 v[82:97], v[60:63], v[150:153], v[34:49]
	v_add_f32_e32 v50, v114, v50
	v_add_f32_e32 v194, v115, v194
	v_add_f32_e32 v195, v116, v195
	v_add_f32_e32 v196, v117, v196
	v_add_f32_e32 v50, v118, v50
	v_add_f32_e32 v194, v119, v194
	v_cvt_pk_bf16_f32 v158, v114, v115
	v_cvt_pk_bf16_f32 v159, v116, v117
	ds_read_b64_tr_b16 v[60:61], v199 offset:28672
	ds_read_b64_tr_b16 v[62:63], v199 offset:29184
	v_mfma_f32_32x32x16_bf16 v[66:81], v[162:165], v[150:153], v[34:49]
	v_add_f32_e32 v195, v120, v195
	v_add_f32_e32 v196, v121, v196
	v_add_f32_e32 v50, v122, v50
	v_add_f32_e32 v194, v123, v194
	v_cvt_pk_bf16_f32 v160, v118, v119
	v_cvt_pk_bf16_f32 v161, v120, v121
	ds_read_b64_tr_b16 v[114:115], v199 offset:25600
	ds_read_b64_tr_b16 v[116:117], v199 offset:26112
	v_mfma_f32_32x32x16_bf16 v[82:97], v[166:169], v[138:141], v[82:97]
	v_add_f32_e32 v195, v124, v195
	v_add_f32_e32 v196, v125, v196
	v_add_f32_e32 v50, v126, v50
	v_add_f32_e32 v194, v127, v194
	v_cvt_pk_bf16_f32 v154, v122, v123
	v_cvt_pk_bf16_f32 v155, v124, v125
	ds_read_b64_tr_b16 v[118:119], v199 offset:29696
	ds_read_b64_tr_b16 v[120:121], v199 offset:30208
	v_mfma_f32_32x32x16_bf16 v[66:81], v[170:173], v[138:141], v[66:81]
	v_add_f32_e32 v195, v128, v195
	v_add_f32_e32 v196, v129, v196
	v_add_f32_e32 v50, v98, v50
	v_add_f32_e32 v194, v99, v194
	v_cvt_pk_bf16_f32 v156, v126, v127
	v_cvt_pk_bf16_f32 v157, v128, v129
	ds_read_b64_tr_b16 v[122:123], v199 offset:26624
	ds_read_b64_tr_b16 v[124:125], v199 offset:27136
	v_mfma_f32_32x32x16_bf16 v[82:97], v[174:177], v[134:137], v[82:97]
	v_add_f32_e32 v195, v100, v195
	v_add_f32_e32 v196, v101, v196
	v_add_f32_e32 v50, v102, v50
	v_add_f32_e32 v194, v103, v194
	v_cvt_pk_bf16_f32 v146, v98, v99
	v_cvt_pk_bf16_f32 v147, v100, v101
	ds_read_b64_tr_b16 v[98:99], v199 offset:30720
	ds_read_b64_tr_b16 v[100:101], v199 offset:31232
	v_mfma_f32_32x32x16_bf16 v[66:81], v[178:181], v[134:137], v[66:81]
	v_add_f32_e32 v195, v104, v195
	v_add_f32_e32 v196, v105, v196
	v_add_f32_e32 v50, v106, v50
	v_add_f32_e32 v194, v107, v194
	v_cvt_pk_bf16_f32 v148, v102, v103
	v_cvt_pk_bf16_f32 v149, v104, v105
	ds_read_b64_tr_b16 v[102:103], v199 offset:27648
	ds_read_b64_tr_b16 v[104:105], v199 offset:28160
	v_mfma_f32_32x32x16_bf16 v[82:97], v[182:185], v[130:133], v[82:97]
	v_add_f32_e32 v195, v108, v195
	v_add_f32_e32 v196, v109, v196
	v_add_f32_e32 v50, v110, v50
	v_add_f32_e32 v194, v111, v194
	v_cvt_pk_bf16_f32 v142, v106, v107
	v_cvt_pk_bf16_f32 v143, v108, v109
	ds_read_b64_tr_b16 v[106:107], v199 offset:31744
	ds_read_b64_tr_b16 v[108:109], v199 offset:32256
	v_mfma_f32_32x32x16_bf16 v[66:81], v[52:55], v[130:133], v[66:81]
	v_add_f32_e32 v195, v112, v195
	v_add_f32_e32 v196, v113, v196
	v_cvt_pk_bf16_f32 v144, v110, v111
	v_cvt_pk_bf16_f32 v145, v112, v113
	s_add_i32 s6, s76, s70
	s_mov_b32 s7, m0
	s_mov_b32 m0, s6
	s_nop 0
	global_load_lds_dwordx4 v197, s[98:99]
	s_mov_b32 m0, s7
	s_add_i32 s6, s31, s71
	s_mov_b32 s7, m0
	s_mov_b32 m0, s6
	s_nop 0
	global_load_lds_dwordx4 v197, s[100:101]
	s_mov_b32 m0, s7
	s_add_u32 s98, s98, 0x2000
	s_addc_u32 s99, s99, 0
	s_add_u32 s100, s100, 0x2000
	s_addc_u32 s101, s101, 0
	s_waitcnt lgkmcnt(14)
	v_mfma_f32_32x32x16_bf16 v[2:17], v[158:161], v[186:189], v[2:17]
	v_exp_f32_e32 v82, v82
	v_exp_f32_e32 v83, v83
	v_exp_f32_e32 v84, v84
	v_exp_f32_e32 v85, v85
	s_waitcnt lgkmcnt(12)
	v_mfma_f32_32x32x16_bf16 v[18:33], v[158:161], v[60:63], v[18:33]
	v_exp_f32_e32 v86, v86
	v_exp_f32_e32 v87, v87
	v_exp_f32_e32 v88, v88
	v_exp_f32_e32 v89, v89
	ds_read_b128 v[190:193], v204
	ds_read_b128 v[186:189], v204 offset:512
	s_waitcnt lgkmcnt(12)
	v_mfma_f32_32x32x16_bf16 v[2:17], v[154:157], v[114:117], v[2:17]
	v_exp_f32_e32 v90, v90
	v_exp_f32_e32 v91, v91
	v_exp_f32_e32 v92, v92
	v_exp_f32_e32 v93, v93
	ds_read_b128 v[182:185], v204 offset:2048
	ds_read_b128 v[178:181], v204 offset:2560
	s_waitcnt lgkmcnt(12)
	v_mfma_f32_32x32x16_bf16 v[18:33], v[154:157], v[118:121], v[18:33]
	v_exp_f32_e32 v94, v94
	v_exp_f32_e32 v95, v95
	v_exp_f32_e32 v96, v96
	v_exp_f32_e32 v97, v97
	ds_read_b128 v[174:177], v204 offset:4096
	ds_read_b128 v[170:173], v204 offset:4608
	s_waitcnt lgkmcnt(12)
	v_mfma_f32_32x32x16_bf16 v[2:17], v[146:149], v[122:125], v[2:17]
	v_exp_f32_e32 v66, v66
	v_exp_f32_e32 v67, v67
	v_exp_f32_e32 v68, v68
	v_exp_f32_e32 v69, v69
	ds_read_b128 v[166:169], v204 offset:6144
	ds_read_b128 v[162:165], v204 offset:6656
	s_waitcnt lgkmcnt(12)
	v_mfma_f32_32x32x16_bf16 v[18:33], v[146:149], v[98:101], v[18:33]
	v_exp_f32_e32 v70, v70
	v_exp_f32_e32 v71, v71
	v_exp_f32_e32 v72, v72
	v_exp_f32_e32 v73, v73
	s_waitcnt lgkmcnt(10)
	v_mfma_f32_32x32x16_bf16 v[2:17], v[142:145], v[102:105], v[2:17]
	v_exp_f32_e32 v74, v74
	v_exp_f32_e32 v75, v75
	v_exp_f32_e32 v76, v76
	v_exp_f32_e32 v77, v77
	s_waitcnt lgkmcnt(8)
	v_mfma_f32_32x32x16_bf16 v[18:33], v[142:145], v[106:109], v[18:33]
	v_exp_f32_e32 v78, v78
	v_exp_f32_e32 v79, v79
	v_exp_f32_e32 v80, v80
	v_exp_f32_e32 v81, v81
	s_add_i32 s6, s31, 0x2000
	s_cmpk_lg_i32 s31, 0x4000
	s_mov_b32 s24, s76
	s_cselect_b32 s76, s6, 0
	s_add_i32 s26, s26, 2
	s_cmp_gt_i32 s26, s91
	s_cbranch_scc1 .Lattn_exit
	s_waitcnt vmcnt(2) lgkmcnt(0)
	s_barrier
.Lattn_cpC:
	ds_read_b64_tr_b16 v[52:53], v200 offset:24576
	ds_read_b64_tr_b16 v[54:55], v200 offset:25088
	v_mfma_f32_32x32x16_bf16 v[114:129], v[190:193], v[150:153], v[34:49]
	v_add_f32_e32 v50, v82, v50
	v_add_f32_e32 v194, v83, v194
	v_add_f32_e32 v195, v84, v195
	v_add_f32_e32 v196, v85, v196
	v_add_f32_e32 v50, v86, v50
	v_add_f32_e32 v194, v87, v194
	v_cvt_pk_bf16_f32 v158, v82, v83
	v_cvt_pk_bf16_f32 v159, v84, v85
	ds_read_b64_tr_b16 v[60:61], v200 offset:28672
	ds_read_b64_tr_b16 v[62:63], v200 offset:29184
	v_mfma_f32_32x32x16_bf16 v[98:113], v[186:189], v[150:153], v[34:49]
	v_add_f32_e32 v195, v88, v195
	v_add_f32_e32 v196, v89, v196
	v_add_f32_e32 v50, v90, v50
	v_add_f32_e32 v194, v91, v194
	v_cvt_pk_bf16_f32 v160, v86, v87
	v_cvt_pk_bf16_f32 v161, v88, v89
	ds_read_b64_tr_b16 v[82:83], v200 offset:25600
	ds_read_b64_tr_b16 v[84:85], v200 offset:26112
	v_mfma_f32_32x32x16_bf16 v[114:129], v[182:185], v[138:141], v[114:129]
	v_add_f32_e32 v195, v92, v195
	v_add_f32_e32 v196, v93, v196
	v_add_f32_e32 v50, v94, v50
	v_add_f32_e32 v194, v95, v194
	v_cvt_pk_bf16_f32 v154, v90, v91
	v_cvt_pk_bf16_f32 v155, v92, v93
	ds_read_b64_tr_b16 v[86:87], v200 offset:29696
	ds_read_b64_tr_b16 v[88:89], v200 offset:30208
	v_mfma_f32_32x32x16_bf16 v[98:113], v[178:181], v[138:141], v[98:113]
	v_add_f32_e32 v195, v96, v195
	v_add_f32_e32 v196, v97, v196
	v_add_f32_e32 v50, v66, v50
	v_add_f32_e32 v194, v67, v194
	v_cvt_pk_bf16_f32 v156, v94, v95
	v_cvt_pk_bf16_f32 v157, v96, v97
	ds_read_b64_tr_b16 v[90:91], v200 offset:26624
	ds_read_b64_tr_b16 v[92:93], v200 offset:27136
	v_mfma_f32_32x32x16_bf16 v[114:129], v[174:177], v[134:137], v[114:129]
	v_add_f32_e32 v195, v68, v195
	v_add_f32_e32 v196, v69, v196
	v_add_f32_e32 v50, v70, v50
	v_add_f32_e32 v194, v71, v194
	v_cvt_pk_bf16_f32 v146, v66, v67
	v_cvt_pk_bf16_f32 v147, v68, v69
	ds_read_b64_tr_b16 v[64:65], v200 offset:30720
	ds_read_b64_tr_b16 v[66:67], v200 offset:31232
	v_mfma_f32_32x32x16_bf16 v[98:113], v[170:173], v[134:137], v[98:113]
	v_add_f32_e32 v195, v72, v195
	v_add_f32_e32 v196, v73, v196
	v_add_f32_e32 v50, v74, v50
	v_add_f32_e32 v194, v75, v194
	v_cvt_pk_bf16_f32 v148, v70, v71
	v_cvt_pk_bf16_f32 v149, v72, v73
	ds_read_b64_tr_b16 v[68:69], v200 offset:27648
	ds_read_b64_tr_b16 v[70:71], v200 offset:28160
	v_mfma_f32_32x32x16_bf16 v[114:129], v[166:169], v[130:133], v[114:129]
	v_add_f32_e32 v195, v76, v195
	v_add_f32_e32 v196, v77, v196
	v_add_f32_e32 v50, v78, v50
	v_add_f32_e32 v194, v79, v194
	v_cvt_pk_bf16_f32 v142, v74, v75
	v_cvt_pk_bf16_f32 v143, v76, v77
	ds_read_b64_tr_b16 v[72:73], v200 offset:31744
	ds_read_b64_tr_b16 v[74:75], v200 offset:32256
	v_mfma_f32_32x32x16_bf16 v[98:113], v[162:165], v[130:133], v[98:113]
	v_add_f32_e32 v195, v80, v195
	v_add_f32_e32 v196, v81, v196
	v_cvt_pk_bf16_f32 v144, v78, v79
	v_cvt_pk_bf16_f32 v145, v80, v81
	s_add_i32 s6, s31, s70
	s_mov_b32 s7, m0
	s_mov_b32 m0, s6
	s_nop 0
	global_load_lds_dwordx4 v197, s[98:99]
	s_mov_b32 m0, s7
	s_add_i32 s6, s76, s71
	s_mov_b32 s7, m0
	s_mov_b32 m0, s6
	s_nop 0
	global_load_lds_dwordx4 v197, s[100:101]
	s_mov_b32 m0, s7
	s_add_u32 s98, s98, 0x2000
	s_addc_u32 s99, s99, 0
	s_add_u32 s100, s100, 0x2000
	s_addc_u32 s101, s101, 0
	s_waitcnt lgkmcnt(14)
	v_mfma_f32_32x32x16_bf16 v[2:17], v[158:161], v[52:55], v[2:17]
	v_exp_f32_e32 v114, v114
	v_exp_f32_e32 v115, v115
	v_exp_f32_e32 v116, v116
	v_exp_f32_e32 v117, v117
	s_waitcnt lgkmcnt(12)
	v_mfma_f32_32x32x16_bf16 v[18:33], v[158:161], v[60:63], v[18:33]
	v_exp_f32_e32 v118, v118
	v_exp_f32_e32 v119, v119
	v_exp_f32_e32 v120, v120
	v_exp_f32_e32 v121, v121
	ds_read_b128 v[60:63], v202
	ds_read_b128 v[162:165], v202 offset:512
	s_waitcnt lgkmcnt(12)
	v_mfma_f32_32x32x16_bf16 v[2:17], v[154:157], v[82:85], v[2:17]
	v_exp_f32_e32 v122, v122
	v_exp_f32_e32 v123, v123
	v_exp_f32_e32 v124, v124
	v_exp_f32_e32 v125, v125
	ds_read_b128 v[166:169], v202 offset:2048
	ds_read_b128 v[170:173], v202 offset:2560
	s_waitcnt lgkmcnt(12)
	v_mfma_f32_32x32x16_bf16 v[18:33], v[154:157], v[86:89], v[18:33]
	v_exp_f32_e32 v126, v126
	v_exp_f32_e32 v127, v127
	v_exp_f32_e32 v128, v128
	v_exp_f32_e32 v129, v129
	ds_read_b128 v[174:177], v202 offset:4096
	ds_read_b128 v[178:181], v202 offset:4608
	s_waitcnt lgkmcnt(12)
	v_mfma_f32_32x32x16_bf16 v[2:17], v[146:149], v[90:93], v[2:17]
	v_exp_f32_e32 v98, v98
	v_exp_f32_e32 v99, v99
	v_exp_f32_e32 v100, v100
	v_exp_f32_e32 v101, v101
	ds_read_b128 v[182:185], v202 offset:6144
	ds_read_b128 v[52:55], v202 offset:6656
	s_waitcnt lgkmcnt(12)
	v_mfma_f32_32x32x16_bf16 v[18:33], v[146:149], v[64:67], v[18:33]
	v_exp_f32_e32 v102, v102
	v_exp_f32_e32 v103, v103
	v_exp_f32_e32 v104, v104
	v_exp_f32_e32 v105, v105
	s_waitcnt lgkmcnt(10)
	v_mfma_f32_32x32x16_bf16 v[2:17], v[142:145], v[68:71], v[2:17]
	v_exp_f32_e32 v106, v106
	v_exp_f32_e32 v107, v107
	v_exp_f32_e32 v108, v108
	v_exp_f32_e32 v109, v109
	s_waitcnt lgkmcnt(8)
	v_mfma_f32_32x32x16_bf16 v[18:33], v[142:145], v[72:75], v[18:33]
	v_exp_f32_e32 v110, v110
	v_exp_f32_e32 v111, v111
	v_exp_f32_e32 v112, v112
	v_exp_f32_e32 v113, v113
	s_add_i32 s6, s76, 0x2000
	s_cmpk_lg_i32 s76, 0x4000
	s_cselect_b32 s31, s6, 0
	s_waitcnt vmcnt(2) lgkmcnt(0)
	s_barrier
;   #define RESC() do{ if(resc){ asm volatile("s_waitcnt lgkmcnt(0)":::"memory"); \
;       _Pragma("unroll") for(int d_=0;d_<2;++d_) _Pragma("unroll") for(int r=0;r<16;++r)o[d_][r]*=wsf[crow(r,hi)]; } }while(0)
;   #define ROT() do{sl_prev=sl_cur;sl_cur=sl_next;sl_next=(sl_next==(NSLOT-1)*SLOTB)?0:sl_next+SLOTB;}while(0)
;   #define ENDW(tt) do{ if((tt)+3<NT){WAIT_BAR(2);} else if((tt)+2<NT){WAIT_BAR(1);} else {WAIT_BAR(0);} }while(0)
; template<int THRL> __device__ __forceinline__ void attn_unit(const bf16*Qu,const bf16*__restrict__ Kh,const bf16*__restrict__ Vh,bf16*Ou,const int NT,const float shift,char*shm){
;     ...
;     STEP(pB0,pB1,pA0,pA1,t,(t+3<NT),(t+1<NT),(t+1<NT));       ENDW(t);   RESC(); ROT();
;     STEP(pA0,pA1,pB0,pB1,t+1,(t+4<NT),(t+2<NT),(t+2<NT));     ENDW(t+1); RESC(); ROT();
;   }
;   STEP(pB0,pB1,pA0,pA1,NT-1,false,false,false); RESC();
;   { float sacc=pB0[0]+pB0[1]; _Pragma("unroll") for(int r=2;r<16;++r)sacc+=pB0[r]; _Pragma("unroll") for(int r=0;r<16;++r)sacc+=pB1[r]; l_reg+=sacc;
	ds_read_b64_tr_b16 v[186:187], v201 offset:24576
	ds_read_b64_tr_b16 v[188:189], v201 offset:25088
	v_mfma_f32_32x32x16_bf16 v[82:97], v[60:63], v[150:153], v[34:49]
	v_add_f32_e32 v50, v114, v50
	v_add_f32_e32 v194, v115, v194
	v_add_f32_e32 v195, v116, v195
	v_add_f32_e32 v196, v117, v196
	v_add_f32_e32 v50, v118, v50
	v_add_f32_e32 v194, v119, v194
	v_cvt_pk_bf16_f32 v158, v114, v115
	v_cvt_pk_bf16_f32 v159, v116, v117
	ds_read_b64_tr_b16 v[60:61], v201 offset:28672
	ds_read_b64_tr_b16 v[62:63], v201 offset:29184
	v_mfma_f32_32x32x16_bf16 v[66:81], v[162:165], v[150:153], v[34:49]
	v_add_f32_e32 v195, v120, v195
	v_add_f32_e32 v196, v121, v196
	v_add_f32_e32 v50, v122, v50
	v_add_f32_e32 v194, v123, v194
	v_cvt_pk_bf16_f32 v160, v118, v119
	v_cvt_pk_bf16_f32 v161, v120, v121
	ds_read_b64_tr_b16 v[114:115], v201 offset:25600
	ds_read_b64_tr_b16 v[116:117], v201 offset:26112
	v_mfma_f32_32x32x16_bf16 v[82:97], v[166:169], v[138:141], v[82:97]
	v_add_f32_e32 v195, v124, v195
	v_add_f32_e32 v196, v125, v196
	v_add_f32_e32 v50, v126, v50
	v_add_f32_e32 v194, v127, v194
	v_cvt_pk_bf16_f32 v154, v122, v123
	v_cvt_pk_bf16_f32 v155, v124, v125
	ds_read_b64_tr_b16 v[118:119], v201 offset:29696
	ds_read_b64_tr_b16 v[120:121], v201 offset:30208
	v_mfma_f32_32x32x16_bf16 v[66:81], v[170:173], v[138:141], v[66:81]
	v_add_f32_e32 v195, v128, v195
	v_add_f32_e32 v196, v129, v196
	v_add_f32_e32 v50, v98, v50
	v_add_f32_e32 v194, v99, v194
	v_cvt_pk_bf16_f32 v156, v126, v127
	v_cvt_pk_bf16_f32 v157, v128, v129
	ds_read_b64_tr_b16 v[122:123], v201 offset:26624
	ds_read_b64_tr_b16 v[124:125], v201 offset:27136
	v_mfma_f32_32x32x16_bf16 v[82:97], v[174:177], v[134:137], v[82:97]
	v_add_f32_e32 v195, v100, v195
	v_add_f32_e32 v196, v101, v196
	v_add_f32_e32 v50, v102, v50
	v_add_f32_e32 v194, v103, v194
	v_cvt_pk_bf16_f32 v146, v98, v99
	v_cvt_pk_bf16_f32 v147, v100, v101
	ds_read_b64_tr_b16 v[98:99], v201 offset:30720
	ds_read_b64_tr_b16 v[100:101], v201 offset:31232
	v_mfma_f32_32x32x16_bf16 v[66:81], v[178:181], v[134:137], v[66:81]
	v_add_f32_e32 v195, v104, v195
	v_add_f32_e32 v196, v105, v196
	v_add_f32_e32 v50, v106, v50
	v_add_f32_e32 v194, v107, v194
	v_cvt_pk_bf16_f32 v148, v102, v103
	v_cvt_pk_bf16_f32 v149, v104, v105
	ds_read_b64_tr_b16 v[102:103], v201 offset:27648
	ds_read_b64_tr_b16 v[104:105], v201 offset:28160
	v_mfma_f32_32x32x16_bf16 v[82:97], v[182:185], v[130:133], v[82:97]
	v_add_f32_e32 v195, v108, v195
	v_add_f32_e32 v196, v109, v196
	v_add_f32_e32 v50, v110, v50
	v_add_f32_e32 v194, v111, v194
	v_cvt_pk_bf16_f32 v142, v106, v107
	v_cvt_pk_bf16_f32 v143, v108, v109
	ds_read_b64_tr_b16 v[106:107], v201 offset:31744
	ds_read_b64_tr_b16 v[108:109], v201 offset:32256
	v_mfma_f32_32x32x16_bf16 v[66:81], v[52:55], v[130:133], v[66:81]
	v_add_f32_e32 v195, v112, v195
	v_add_f32_e32 v196, v113, v196
	v_cvt_pk_bf16_f32 v144, v110, v111
	v_cvt_pk_bf16_f32 v145, v112, v113
	s_add_i32 s6, s76, s70
	s_mov_b32 s7, m0
	s_mov_b32 m0, s6
	s_nop 0
	global_load_lds_dwordx4 v197, s[98:99]
	s_mov_b32 m0, s7
	s_add_i32 s6, s31, s71
	s_mov_b32 s7, m0
	s_mov_b32 m0, s6
	s_nop 0
	global_load_lds_dwordx4 v197, s[100:101]
	s_mov_b32 m0, s7
	s_add_u32 s98, s98, 0x2000
	s_addc_u32 s99, s99, 0
	s_add_u32 s100, s100, 0x2000
	s_addc_u32 s101, s101, 0
	s_waitcnt lgkmcnt(14)
	v_mfma_f32_32x32x16_bf16 v[2:17], v[158:161], v[186:189], v[2:17]
	v_exp_f32_e32 v82, v82
	v_exp_f32_e32 v83, v83
	v_exp_f32_e32 v84, v84
	v_exp_f32_e32 v85, v85
	s_waitcnt lgkmcnt(12)
	v_mfma_f32_32x32x16_bf16 v[18:33], v[158:161], v[60:63], v[18:33]
	v_exp_f32_e32 v86, v86
	v_exp_f32_e32 v87, v87
	v_exp_f32_e32 v88, v88
	v_exp_f32_e32 v89, v89
	ds_read_b128 v[190:193], v203
	ds_read_b128 v[186:189], v203 offset:512
	s_waitcnt lgkmcnt(12)
	v_mfma_f32_32x32x16_bf16 v[2:17], v[154:157], v[114:117], v[2:17]
	v_exp_f32_e32 v90, v90
	v_exp_f32_e32 v91, v91
	v_exp_f32_e32 v92, v92
	v_exp_f32_e32 v93, v93
	ds_read_b128 v[182:185], v203 offset:2048
	ds_read_b128 v[178:181], v203 offset:2560
	s_waitcnt lgkmcnt(12)
	v_mfma_f32_32x32x16_bf16 v[18:33], v[154:157], v[118:121], v[18:33]
	v_exp_f32_e32 v94, v94
	v_exp_f32_e32 v95, v95
	v_exp_f32_e32 v96, v96
	v_exp_f32_e32 v97, v97
	ds_read_b128 v[174:177], v203 offset:4096
	ds_read_b128 v[170:173], v203 offset:4608
	s_waitcnt lgkmcnt(12)
	v_mfma_f32_32x32x16_bf16 v[2:17], v[146:149], v[122:125], v[2:17]
	v_exp_f32_e32 v66, v66
	v_exp_f32_e32 v67, v67
	v_exp_f32_e32 v68, v68
	v_exp_f32_e32 v69, v69
	ds_read_b128 v[166:169], v203 offset:6144
	ds_read_b128 v[162:165], v203 offset:6656
	s_waitcnt lgkmcnt(12)
	v_mfma_f32_32x32x16_bf16 v[18:33], v[146:149], v[98:101], v[18:33]
	v_exp_f32_e32 v70, v70
	v_exp_f32_e32 v71, v71
	v_exp_f32_e32 v72, v72
	v_exp_f32_e32 v73, v73
	s_waitcnt lgkmcnt(10)
	v_mfma_f32_32x32x16_bf16 v[2:17], v[142:145], v[102:105], v[2:17]
	v_exp_f32_e32 v74, v74
	v_exp_f32_e32 v75, v75
	v_exp_f32_e32 v76, v76
	v_exp_f32_e32 v77, v77
	s_waitcnt lgkmcnt(8)
	v_mfma_f32_32x32x16_bf16 v[18:33], v[142:145], v[106:109], v[18:33]
	v_exp_f32_e32 v78, v78
	v_exp_f32_e32 v79, v79
	v_exp_f32_e32 v80, v80
	v_exp_f32_e32 v81, v81
	s_add_i32 s6, s31, 0x2000
	s_cmpk_lg_i32 s31, 0x4000
	s_mov_b32 s24, s76
	s_cselect_b32 s76, s6, 0
	s_add_i32 s26, s26, 2
	s_cmp_gt_i32 s26, s91
	s_cbranch_scc0 .Lattn_rot
.Lattn_exit:
	s_waitcnt vmcnt(2) lgkmcnt(0)
	s_barrier
	v_add_f32_e32 v50, v50, v194
	v_add_f32_e32 v50, v50, v195
	v_add_f32_e32 v50, v50, v196
	s_mov_b32 s4, s24
	s_add_i32 s5, s26, -5
	s_branch .LBB0_621
